# P1 slack conversion: only the w_gate items (2 of ~7 per wave) run with their 32 loads in flight - balances the conversion workgroups against the 7-unit GEMM workgroups
# speedup vs baseline: 1.0084x; 1.0031x over previous
; __device__ __forceinline__ void tr_item(const float* W, int N, int k0, int n0, bf16* WT, int dst_pitch, int dst_row0, int dst_k0, int ncopies, int copy_stride, LAS float* scr, int lane) {
; #pragma unroll 8
;     for (int i = 0; i < 32; ++i) { const int kk = 2 * i + (lane >> 5); scr[kk * 33 + (lane & 31)] = __builtin_nontemporal_load(W + (size_t)(k0 + kk) * N + n0 + (lane & 31)); }
.LBB0_190:
	v_add_u32_e32 v30, s53, v19
	v_add_u32_e32 v31, 6, v30
	v_add_u32_e32 v32, 8, v30
	v_add_u32_e32 v34, 10, v30
	v_add_u32_e32 v50, 12, v30
	v_add_u32_e32 v52, 14, v30
	v_mad_i64_i32 v[30:31], s[54:55], v31, s49, v[20:21]
	v_mad_i64_i32 v[32:33], s[54:55], v32, s49, v[20:21]
	v_mad_i64_i32 v[34:35], s[54:55], v34, s49, v[20:21]
	global_load_dword v176, v[26:27], off nt
	global_load_dword v177, v[24:25], off nt
	global_load_dword v178, v[22:23], off nt
	v_mad_i64_i32 v[50:51], s[54:55], v50, s49, v[20:21]
	v_mad_i64_i32 v[52:53], s[54:55], v52, s49, v[20:21]
	global_load_dword v179, v[30:31], off nt
	global_load_dword v180, v[32:33], off nt
	global_load_dword v181, v[34:35], off nt
	global_load_dword v182, v[50:51], off nt
	global_load_dword v183, v[52:53], off nt
	s_add_i32 s53, s53, 16
	v_lshl_add_u64 v[22:23], v[22:23], 0, s[6:7]
	v_lshl_add_u64 v[24:25], v[24:25], 0, s[6:7]
	v_lshl_add_u64 v[26:27], v[26:27], 0, s[6:7]
	v_add_u32_e32 v30, s53, v19
	v_add_u32_e32 v31, 6, v30
	v_add_u32_e32 v32, 8, v30
	v_add_u32_e32 v34, 10, v30
	v_add_u32_e32 v50, 12, v30
	v_add_u32_e32 v52, 14, v30
	v_mad_i64_i32 v[30:31], s[54:55], v31, s49, v[20:21]
	v_mad_i64_i32 v[32:33], s[54:55], v32, s49, v[20:21]
	v_mad_i64_i32 v[34:35], s[54:55], v34, s49, v[20:21]
	global_load_dword v184, v[26:27], off nt
	global_load_dword v185, v[24:25], off nt
	global_load_dword v186, v[22:23], off nt
	v_mad_i64_i32 v[50:51], s[54:55], v50, s49, v[20:21]
	v_mad_i64_i32 v[52:53], s[54:55], v52, s49, v[20:21]
	global_load_dword v187, v[30:31], off nt
	global_load_dword v188, v[32:33], off nt
	global_load_dword v189, v[34:35], off nt
	global_load_dword v190, v[50:51], off nt
	global_load_dword v191, v[52:53], off nt
	s_add_i32 s53, s53, 16
	v_lshl_add_u64 v[22:23], v[22:23], 0, s[6:7]
	v_lshl_add_u64 v[24:25], v[24:25], 0, s[6:7]
	v_lshl_add_u64 v[26:27], v[26:27], 0, s[6:7]
	v_add_u32_e32 v30, s53, v19
	v_add_u32_e32 v31, 6, v30
	v_add_u32_e32 v32, 8, v30
	v_add_u32_e32 v34, 10, v30
	v_add_u32_e32 v50, 12, v30
	v_add_u32_e32 v52, 14, v30
	v_mad_i64_i32 v[30:31], s[54:55], v31, s49, v[20:21]
	v_mad_i64_i32 v[32:33], s[54:55], v32, s49, v[20:21]
	v_mad_i64_i32 v[34:35], s[54:55], v34, s49, v[20:21]
	global_load_dword v192, v[26:27], off nt
	global_load_dword v193, v[24:25], off nt
	global_load_dword v194, v[22:23], off nt
	v_mad_i64_i32 v[50:51], s[54:55], v50, s49, v[20:21]
	v_mad_i64_i32 v[52:53], s[54:55], v52, s49, v[20:21]
	global_load_dword v195, v[30:31], off nt
	global_load_dword v196, v[32:33], off nt
	global_load_dword v197, v[34:35], off nt
	global_load_dword v198, v[50:51], off nt
	global_load_dword v199, v[52:53], off nt
	s_add_i32 s53, s53, 16
	v_lshl_add_u64 v[22:23], v[22:23], 0, s[6:7]
	v_lshl_add_u64 v[24:25], v[24:25], 0, s[6:7]
	v_lshl_add_u64 v[26:27], v[26:27], 0, s[6:7]
	v_add_u32_e32 v30, s53, v19
	v_add_u32_e32 v31, 6, v30
	v_add_u32_e32 v32, 8, v30
	v_add_u32_e32 v34, 10, v30
	v_add_u32_e32 v50, 12, v30
	v_add_u32_e32 v52, 14, v30
	v_mad_i64_i32 v[30:31], s[54:55], v31, s49, v[20:21]
	v_mad_i64_i32 v[32:33], s[54:55], v32, s49, v[20:21]
	v_mad_i64_i32 v[34:35], s[54:55], v34, s49, v[20:21]
	global_load_dword v200, v[26:27], off nt
	global_load_dword v201, v[24:25], off nt
	global_load_dword v202, v[22:23], off nt
	v_mad_i64_i32 v[50:51], s[54:55], v50, s49, v[20:21]
	v_mad_i64_i32 v[52:53], s[54:55], v52, s49, v[20:21]
	global_load_dword v203, v[30:31], off nt
	global_load_dword v204, v[32:33], off nt
	global_load_dword v205, v[34:35], off nt
	global_load_dword v206, v[50:51], off nt
	global_load_dword v207, v[52:53], off nt
	s_add_i32 s53, s53, 16
	v_lshl_add_u64 v[22:23], v[22:23], 0, s[6:7]
	v_lshl_add_u64 v[24:25], v[24:25], 0, s[6:7]
	v_lshl_add_u64 v[26:27], v[26:27], 0, s[6:7]
	s_waitcnt vmcnt(24)
; #define LAS __attribute__((address_space(3)))
; __device__ __forceinline__ unsigned cvtpk(float lo, float hi) { f32x2_t v = {lo, hi}; bf16x2_t b = __builtin_convertvector(v, bf16x2_t); return __builtin_bit_cast(unsigned, b); }
; __device__ __forceinline__ void tr_item(const float* W, int N, int k0, int n0, bf16* WT, int dst_pitch, int dst_row0, int dst_k0, int ncopies, int copy_stride, LAS float* scr, int lane) {
;     ...
;     for (int i = 0; i < 32; ++i) { const int kk = 2 * i + (lane >> 5); scr[kk * 33 + (lane & 31)] = __builtin_nontemporal_load(W + (size_t)(k0 + kk) * N + n0 + (lane & 31)); }
;     asm volatile("s_waitcnt lgkmcnt(0)" ::: "memory");
;     const int c = lane & 7;
; #pragma unroll
;     for (int j = 0; j < 4; ++j) { const int n = (lane >> 3) + 8 * j; const LAS float* s = scr + (8 * c) * 33 + n;
;         u32x4 o; o.x = cvtpk(s[0 * 33], s[1 * 33]); o.y = cvtpk(s[2 * 33], s[3 * 33]); o.z = cvtpk(s[4 * 33], s[5 * 33]); o.w = cvtpk(s[6 * 33], s[7 * 33]);
;         bf16* dst = WT + (size_t)(dst_row0 + n0 + n) * dst_pitch + dst_k0 + k0 + 8 * c;
;         for (int cp = 0; cp < ncopies; ++cp) *(u32x4*)(dst + (size_t)cp * copy_stride) = o; }
	v_add_u32_e32 v35, 0x400, v28
	ds_write2_b32 v28, v176, v177 offset1:66
	ds_write2_b32 v28, v178, v179 offset0:132 offset1:198
	ds_write2_b32 v35, v180, v181 offset0:8 offset1:74
	ds_write2_b32 v35, v182, v183 offset0:140 offset1:206
	v_add_u32_e32 v28, 0x840, v28
	s_waitcnt vmcnt(16)
	v_add_u32_e32 v35, 0x400, v28
	ds_write2_b32 v28, v184, v185 offset1:66
	ds_write2_b32 v28, v186, v187 offset0:132 offset1:198
	ds_write2_b32 v35, v188, v189 offset0:8 offset1:74
	ds_write2_b32 v35, v190, v191 offset0:140 offset1:206
	v_add_u32_e32 v28, 0x840, v28
	s_waitcnt vmcnt(8)
	v_add_u32_e32 v35, 0x400, v28
	ds_write2_b32 v28, v192, v193 offset1:66
	ds_write2_b32 v28, v194, v195 offset0:132 offset1:198
	ds_write2_b32 v35, v196, v197 offset0:8 offset1:74
	ds_write2_b32 v35, v198, v199 offset0:140 offset1:206
	v_add_u32_e32 v28, 0x840, v28
	s_waitcnt vmcnt(0)
	v_add_u32_e32 v35, 0x400, v28
	ds_write2_b32 v28, v200, v201 offset1:66
	ds_write2_b32 v28, v202, v203 offset0:132 offset1:198
	ds_write2_b32 v35, v204, v205 offset0:8 offset1:74
	ds_write2_b32 v35, v206, v207 offset0:140 offset1:206
	v_add_u32_e32 v28, 0x840, v28
	s_lshl_b32 s21, s52, 6
	s_and_b64 s[22:23], s[22:23], exec
	s_cselect_b32 s22, 0x80, 0
	s_and_b32 s21, s21, 0x1f00
	s_waitcnt lgkmcnt(0)
	s_and_b32 s4, s4, 0x60
	s_or_b32 s21, s21, s22
	ds_read2_b32 v[24:25], v37 offset0:33 offset1:41
	ds_read2_b32 v[26:27], v37 offset1:8
	ds_read2_b32 v[28:29], v37 offset0:66 offset1:74
	ds_read2_b32 v[30:31], v37 offset0:99 offset1:107
	ds_read2_b32 v[32:33], v37 offset0:132 offset1:140
	ds_read2_b32 v[34:35], v37 offset0:165 offset1:173
	ds_read2_b32 v[50:51], v37 offset0:198 offset1:206
	ds_read2_b32 v[52:53], v37 offset0:231 offset1:239
	s_or_b32 s4, s21, s4
	v_add_u32_e32 v56, s4, v36
	s_mov_b32 s21, s5
	v_ashrrev_i32_e32 v57, 31, v56
	v_lshl_add_u64 v[54:55], s[20:21], 1, v[4:5]
	v_lshlrev_b64 v[56:57], 11, v[56:57]
	s_waitcnt lgkmcnt(6)
	v_cvt_pk_bf16_f32 v20, v26, v24
	s_waitcnt lgkmcnt(4)
	v_cvt_pk_bf16_f32 v21, v28, v30
	s_waitcnt lgkmcnt(2)
	v_cvt_pk_bf16_f32 v22, v32, v34
	s_waitcnt lgkmcnt(0)
	v_cvt_pk_bf16_f32 v23, v50, v52
	v_lshl_add_u64 v[56:57], v[54:55], 0, v[56:57]
	v_add_u32_e32 v24, s4, v38
	global_store_dwordx4 v[56:57], v[20:23], off
	s_mov_b64 s[20:21], 0
	s_nop 0
	v_cvt_pk_bf16_f32 v20, v27, v25
	v_ashrrev_i32_e32 v25, 31, v24
	v_cvt_pk_bf16_f32 v21, v29, v31
	v_cvt_pk_bf16_f32 v22, v33, v35
	v_cvt_pk_bf16_f32 v23, v51, v53
	v_lshlrev_b64 v[24:25], 11, v[24:25]
	ds_read2_b32 v[26:27], v37 offset0:49 offset1:57
	ds_read2_b32 v[28:29], v37 offset0:16 offset1:24
	ds_read2_b32 v[30:31], v37 offset0:82 offset1:90
	ds_read2_b32 v[32:33], v37 offset0:115 offset1:123
	ds_read2_b32 v[34:35], v37 offset0:148 offset1:156
	ds_read2_b32 v[50:51], v37 offset0:181 offset1:189
	ds_read2_b32 v[52:53], v37 offset0:214 offset1:222
	ds_read2_b32 v[56:57], v37 offset0:247 offset1:255
	v_lshl_add_u64 v[24:25], v[54:55], 0, v[24:25]
	global_store_dwordx4 v[24:25], v[20:23], off
	v_add_u32_e32 v24, s4, v39
	v_ashrrev_i32_e32 v25, 31, v24
	v_lshlrev_b64 v[24:25], 11, v[24:25]
	s_waitcnt lgkmcnt(6)
	v_cvt_pk_bf16_f32 v20, v28, v26
	s_waitcnt lgkmcnt(4)
	v_cvt_pk_bf16_f32 v21, v30, v32
	s_waitcnt lgkmcnt(2)
	v_cvt_pk_bf16_f32 v22, v34, v50
	s_waitcnt lgkmcnt(0)
	v_cvt_pk_bf16_f32 v23, v52, v56
	v_lshl_add_u64 v[24:25], v[54:55], 0, v[24:25]
	global_store_dwordx4 v[24:25], v[20:23], off
	v_add_u32_e32 v24, s4, v40
	v_ashrrev_i32_e32 v25, 31, v24
	v_lshlrev_b64 v[24:25], 11, v[24:25]
	v_cvt_pk_bf16_f32 v20, v29, v27
	v_cvt_pk_bf16_f32 v21, v31, v33
	v_cvt_pk_bf16_f32 v22, v35, v51
	v_cvt_pk_bf16_f32 v23, v53, v57
	v_lshl_add_u64 v[24:25], v[54:55], 0, v[24:25]
	global_store_dwordx4 v[24:25], v[20:23], off
	s_waitcnt lgkmcnt(0)
